# g1_plus_mixer_counted_vmcnt
# baseline (speedup 1.0000x reference)
; DEVI float logsigmoidf_(float x) { return fminf(x, 0.f) - 0.6931471805599453f * __builtin_amdgcn_logf(1.0f + __builtin_amdgcn_exp2f(-fabsf(x) * LOG2E)); }
; __device__ __forceinline__ void mlstm_item8(const Params& p, unsigned char* lds, int item) {
;     ...
;     if (w == 0) {
;       const bool valid = (c > 0) || (lane >= 48);
;       const float lf = valid ? logsigmoidf_(gf + bF) : 0.f;
;       const float li = valid ? gi + bI : -INFINITY;
;       float bb = lf;
; #pragma unroll
;       for (int o = 1; o < 64; o <<= 1) { const float t = __shfl_up(bb, o); if (lane >= o) bb += t; }
;       const float g = __shfl(bb, 63);
;       const float cs = li - bb;
;       float pm = cs;
; #pragma unroll
;       for (int o = 1; o < 64; o <<= 1) { const float t = __shfl_up(pm, o); if (lane >= o) pm = fmaxf(pm, t); }
;       const float pmax = __shfl(pm, 63);
;       const float inter = bb + m_state, mrow = fmaxf(inter, bb + pm);
;       rowt[lane] = bb - mrow; cols[lane] = cs; winter[lane] = __expf(inter - mrow); emr[lane] = __expf(-mrow);
;       const float m_new = fmaxf(g + m_state, g + pmax);
;       wkv[lane] = __expf(g + cs - m_new);
;       if (lane == 0) scal[0] = __expf(g + m_state - m_new);
;       m_state = m_new;
;     }
.LBB0_351:
	s_cmpk_lt_u32 s20, 0x80
	s_cbranch_scc0 .Lml_fast
	s_waitcnt vmcnt(0)
.Lml_fast:
	v_cmp_ne_u32_e64 s[0:1], 1, v150
	s_andn2_b64 vcc, exec, s[54:55]
	s_cbranch_vccnz .LBB0_357
	s_cmp_lg_u32 s20, 0
	s_cselect_b64 s[44:45], -1, 0
	s_or_b64 vcc, s[2:3], s[44:45]
	v_mov_b32_e32 v36, 0
	s_and_saveexec_b64 s[44:45], vcc
	s_cbranch_execz .LBB0_354
	s_waitcnt vmcnt(8)
	v_add_f32_e32 v36, v83, v85
	s_mov_b32 s11, 0xbfb8aa3b
	v_mul_f32_e64 v37, |v36|, s11
	v_exp_f32_e32 v37, v37
	v_min_f32_e32 v36, 0, v36
	v_add_f32_e32 v37, 1.0, v37
	v_log_f32_e32 v37, v37
	s_nop 0
	v_fmac_f32_e32 v36, 0xbf317218, v37
.LBB0_354:
	s_or_b64 exec, exec, s[44:45]
	v_cmp_lt_i32_e64 s[44:45], v73, v72
	s_waitcnt vmcnt(9)
	v_add_f32_e32 v44, v82, v84
	v_cndmask_b32_e32 v44, v80, v44, vcc
	v_cndmask_b32_e64 v37, v73, v71, s[44:45]
	v_lshlrev_b32_e32 v37, 2, v37
	ds_bpermute_b32 v38, v37, v36
	v_cmp_lt_i32_e64 s[44:45], v74, v72
	s_waitcnt lgkmcnt(0)
	v_add_f32_e32 v38, v36, v38
	v_cndmask_b32_e64 v39, v74, v71, s[44:45]
	v_lshlrev_b32_e32 v39, 2, v39
	v_cndmask_b32_e64 v36, v38, v36, s[4:5]
	ds_bpermute_b32 v38, v39, v36
	v_cmp_lt_i32_e64 s[44:45], v75, v72
	s_waitcnt lgkmcnt(0)
	v_add_f32_e32 v38, v36, v38
	v_cndmask_b32_e64 v40, v75, v71, s[44:45]
	v_lshlrev_b32_e32 v40, 2, v40
	v_cndmask_b32_e64 v36, v38, v36, s[34:35]
	ds_bpermute_b32 v38, v40, v36
	v_cmp_lt_i32_e64 s[44:45], v76, v72
	s_waitcnt lgkmcnt(0)
	v_add_f32_e32 v38, v36, v38
	v_cndmask_b32_e64 v41, v76, v71, s[44:45]
	v_lshlrev_b32_e32 v41, 2, v41
	v_cndmask_b32_e64 v36, v38, v36, s[36:37]
	ds_bpermute_b32 v38, v41, v36
	v_cmp_lt_i32_e64 s[44:45], v77, v72
	s_waitcnt lgkmcnt(0)
	v_add_f32_e32 v38, v36, v38
	v_cndmask_b32_e64 v42, v77, v71, s[44:45]
	v_lshlrev_b32_e32 v42, 2, v42
	v_cndmask_b32_e64 v36, v38, v36, s[38:39]
	ds_bpermute_b32 v38, v42, v36
	v_cmp_lt_i32_e64 s[44:45], v79, v72
	s_waitcnt lgkmcnt(0)
	v_add_f32_e32 v38, v36, v38
	v_cndmask_b32_e64 v43, v79, v71, s[44:45]
	v_lshlrev_b32_e32 v43, 2, v43
	v_cndmask_b32_e64 v36, v38, v36, s[14:15]
	ds_bpermute_b32 v38, v43, v36
	s_waitcnt lgkmcnt(0)
	v_add_f32_e32 v38, v36, v38
	v_cndmask_b32_e64 v38, v38, v36, s[40:41]
	v_sub_f32_e32 v44, v44, v38
	ds_bpermute_b32 v36, v37, v44
	s_waitcnt lgkmcnt(0)
	v_max_f32_e32 v36, v36, v36
	v_max_f32_e32 v36, v44, v36
	v_cndmask_b32_e64 v36, v36, v44, s[4:5]
	ds_bpermute_b32 v37, v39, v36
	ds_bpermute_b32 v39, v81, v38
	s_waitcnt lgkmcnt(1)
	v_max_f32_e32 v37, v37, v37
	v_max_f32_e32 v37, v36, v37
	v_cndmask_b32_e64 v36, v37, v36, s[34:35]
	ds_bpermute_b32 v37, v40, v36
	s_waitcnt lgkmcnt(0)
	v_max_f32_e32 v37, v37, v37
	v_max_f32_e32 v37, v36, v37
	v_cndmask_b32_e64 v36, v37, v36, s[36:37]
	ds_bpermute_b32 v37, v41, v36
	v_add_f32_e32 v41, v57, v38
	s_waitcnt lgkmcnt(0)
	v_max_f32_e32 v37, v37, v37
	v_max_f32_e32 v37, v36, v37
	v_cndmask_b32_e64 v36, v37, v36, s[38:39]
	ds_bpermute_b32 v37, v42, v36
	s_waitcnt lgkmcnt(0)
	v_max_f32_e32 v37, v37, v37
	v_max_f32_e32 v37, v36, v37
	v_cndmask_b32_e64 v37, v37, v36, s[14:15]
	ds_bpermute_b32 v40, v43, v37
	v_max_f32_e32 v42, v37, v37
	v_add_f32_e32 v36, v57, v39
	s_waitcnt lgkmcnt(0)
	v_max_f32_e32 v40, v40, v40
	v_max_f32_e32 v40, v42, v40
	v_cndmask_b32_e64 v37, v40, v37, s[40:41]
	ds_bpermute_b32 v40, v81, v37
	v_add_f32_e32 v37, v38, v37
	v_max_f32_e32 v37, v41, v37
	v_sub_f32_e32 v38, v38, v37
	v_sub_f32_e32 v41, v41, v37
	s_waitcnt lgkmcnt(0)
	v_add_f32_e32 v40, v39, v40
	ds_write_b32 v86, v38
	v_mul_f32_e32 v38, 0x3fb8aa3b, v41
	v_max_f32_e32 v57, v36, v40
	v_add_f32_e32 v39, v44, v39
	v_mul_f32_e32 v37, 0xbfb8aa3b, v37
	v_exp_f32_e32 v38, v38
	v_sub_f32_e32 v39, v39, v57
	v_exp_f32_e32 v37, v37
	v_mul_f32_e32 v39, 0x3fb8aa3b, v39
	v_exp_f32_e32 v39, v39
	ds_write_b32 v87, v44
	ds_write_b32 v88, v38
	ds_write_b32 v89, v37
	ds_write_b32 v90, v39
	s_and_saveexec_b64 s[44:45], s[4:5]
	s_cbranch_execz .LBB0_356
	v_sub_f32_e32 v36, v36, v57
	v_mul_f32_e32 v36, 0x3fb8aa3b, v36
	v_exp_f32_e32 v36, v36
	ds_write_b32 v78, v36

; DEVI unsigned pk_bf16(float lo, float hi) { unsigned r; asm("v_cvt_pk_bf16_f32 %0, %1, %2" : "=v"(r) : "v"(lo), "v"(hi)); return r; }
; DEVI float bf_lo(unsigned u) { return __uint_as_float(u << 16); }
; DEVI float bf_hi(unsigned u) { return __uint_as_float(u & 0xffff0000u); }
; #define LBAR() do { asm volatile("s_waitcnt lgkmcnt(0)" ::: "memory"); __builtin_amdgcn_s_barrier(); asm volatile("" ::: "memory"); } while (0)
; __device__ __forceinline__ void mlstm_item8(const Params& p, unsigned char* lds, int item) {
;     ...
;   auto prefetch = [&](int c) {
;     const int tok = 64 * c - 48 + lane;
;     if (tok >= 0) { const bf16_t* sp = Z + (size_t)(b * T + tok) * LDZE + hh * 128 + (2 * w) * 8; rq[0] = *(const uint4*)sp; rq[1] = *(const uint4*)(sp + 8); rk[0] = *(const uint4*)(sp + 512); rk[1] = *(const uint4*)(sp + 520);
;       rv = *(const uint4*)(Z + (size_t)(b * T + tok) * LDZE + 1024 + hh * 256 + s2 * 64 + w * 8); }
;     else { rq[0] = rq[1] = rk[0] = rk[1] = rv = make_uint4(0, 0, 0, 0); }
;     if (w == 0 && tok >= 0) { gi = GE[(size_t)(b * T + tok) * 8 + hh]; gf = GE[(size_t)(b * T + tok) * 8 + 4 + hh]; }
;     ...
; #pragma unroll
;     for (int i = 0; i < 2; ++i) { *(uint4*)(Qs + lane * 136 + (2 * w + i) * 8) = rq[i]; *(uint4*)(Ks + lane * 136 + (2 * w + i) * 8) = rk[i]; }
;     { const unsigned vv[4] = {rv.x, rv.y, rv.z, rv.w};
; #pragma unroll
;       for (int j = 0; j < 4; ++j) { Vt[(w * 8 + 2 * j) * 72 + lane] = (bf16_t)(vv[j] & 0xffffu); Vt[(w * 8 + 2 * j + 1) * 72 + lane] = (bf16_t)(vv[j] >> 16); } }
; #pragma unroll
;     for (int et = 0; et < 4; ++et) { uint2 wv; wv.x = pk_bf16(Cacc[et][0], Cacc[et][1]); wv.y = pk_bf16(Cacc[et][2], Cacc[et][3]);
;       *(uint2*)(Ct + (16 * et + fr) * 136 + 16 * w + 4 * fq) = wv; }
;     LBAR();
;     { const float wks = wkv[lane];
; #pragma unroll
;       for (int i = 0; i < 2; ++i) { const unsigned kk[4] = {rk[i].x, rk[i].y, rk[i].z, rk[i].w};
; #pragma unroll
;         for (int j = 0; j < 4; ++j) { const unsigned pr = pk_bf16(bf_lo(kk[j]) * wks, bf_hi(kk[j]) * wks);
;           Kt[((2 * w + i) * 8 + 2 * j) * 72 + lane] = (bf16_t)(pr & 0xffffu); Kt[((2 * w + i) * 8 + 2 * j + 1) * 72 + lane] = (bf16_t)(pr >> 16); } } }
;     if (c + 1 < 65) prefetch(c + 1);
.LBB0_357:
	v_cvt_pk_bf16_f32 v36, v24, v25
	v_cvt_pk_bf16_f32 v37, v26, v27
	s_waitcnt vmcnt(11)
	ds_write_b128 v124, v[4:7]
	s_waitcnt vmcnt(9)
	ds_write_b128 v124, v[12:15] offset:17408
	ds_write_b128 v124, v[0:3] offset:16
	ds_write_b128 v124, v[8:11] offset:17424
	s_waitcnt vmcnt(8)
	ds_write_b16 v125, v16 offset:53248
	ds_write_b16_d16_hi v126, v16 offset:53392
	ds_write_b16 v125, v17 offset:53536
	ds_write_b16_d16_hi v126, v17 offset:53680
	ds_write_b16 v125, v18 offset:53824
	ds_write_b16_d16_hi v126, v18 offset:53968
	ds_write_b16 v125, v19 offset:54112
	ds_write_b16_d16_hi v126, v19 offset:54256
	ds_write_b64 v151, v[36:37] offset:62464
	v_cvt_pk_bf16_f32 v36, v28, v29
	v_cvt_pk_bf16_f32 v37, v30, v31
	ds_write_b64 v152, v[36:37] offset:62464
	v_cvt_pk_bf16_f32 v36, v20, v21
	v_cvt_pk_bf16_f32 v37, v22, v23
	ds_write_b64 v153, v[36:37] offset:62464
	v_cvt_pk_bf16_f32 v36, v32, v33
	v_cvt_pk_bf16_f32 v37, v34, v35
	ds_write_b64 v154, v[36:37] offset:62464
	s_waitcnt lgkmcnt(0)
	s_barrier
	ds_read_b32 v36, v90
	v_lshlrev_b32_e32 v37, 16, v12
	v_and_b32_e32 v38, 0xffff0000, v12
	s_cmpk_eq_i32 s20, 0x1000
	s_waitcnt lgkmcnt(0)
	v_mul_f32_e32 v37, v36, v37
	v_mul_f32_e32 v38, v36, v38
	v_cvt_pk_bf16_f32 v37, v37, v38
	ds_write_b16 v127, v37 offset:34816
	ds_write_b16_d16_hi v129, v37 offset:34960
	v_lshlrev_b32_e32 v37, 16, v13
	v_mul_f32_e32 v37, v36, v37
	v_and_b32_e32 v38, 0xffff0000, v13
	v_mul_f32_e32 v38, v36, v38
	v_cvt_pk_bf16_f32 v37, v37, v38
	ds_write_b16 v127, v37 offset:35104
	ds_write_b16_d16_hi v129, v37 offset:35248
	v_lshlrev_b32_e32 v37, 16, v14
	v_mul_f32_e32 v37, v36, v37
	v_and_b32_e32 v38, 0xffff0000, v14
	v_mul_f32_e32 v38, v36, v38
	v_cvt_pk_bf16_f32 v37, v37, v38
	ds_write_b16 v127, v37 offset:35392
	ds_write_b16_d16_hi v129, v37 offset:35536
	v_lshlrev_b32_e32 v37, 16, v15
	v_mul_f32_e32 v37, v36, v37
	v_and_b32_e32 v38, 0xffff0000, v15
	v_mul_f32_e32 v38, v36, v38
	v_cvt_pk_bf16_f32 v37, v37, v38
	ds_write_b16 v127, v37 offset:35680
	ds_write_b16_d16_hi v129, v37 offset:35824
	v_lshlrev_b32_e32 v37, 16, v8
	v_mul_f32_e32 v37, v36, v37
	v_and_b32_e32 v38, 0xffff0000, v8
	v_mul_f32_e32 v38, v36, v38
	v_cvt_pk_bf16_f32 v37, v37, v38
	ds_write_b16 v130, v37 offset:34816
	ds_write_b16_d16_hi v131, v37 offset:34960
	v_lshlrev_b32_e32 v37, 16, v9
	v_mul_f32_e32 v37, v36, v37
	v_and_b32_e32 v38, 0xffff0000, v9
	v_mul_f32_e32 v38, v36, v38
	v_cvt_pk_bf16_f32 v37, v37, v38
	ds_write_b16 v127, v37 offset:36256
	ds_write_b16_d16_hi v129, v37 offset:36400
	v_lshlrev_b32_e32 v37, 16, v10
	v_mul_f32_e32 v37, v36, v37
	v_and_b32_e32 v38, 0xffff0000, v10
	v_mul_f32_e32 v38, v36, v38
	v_cvt_pk_bf16_f32 v37, v37, v38
	ds_write_b16 v127, v37 offset:36544
	ds_write_b16_d16_hi v129, v37 offset:36688
	v_lshlrev_b32_e32 v37, 16, v11
	v_and_b32_e32 v38, 0xffff0000, v11
	v_mul_f32_e32 v37, v36, v37
	v_mul_f32_e32 v36, v36, v38
	v_cvt_pk_bf16_f32 v36, v37, v36
	ds_write_b16 v127, v36 offset:36832
	ds_write_b16_d16_hi v129, v36 offset:36976
	s_cbranch_scc1 .LBB0_360
	v_add_u32_e32 v36, s20, v149
	v_mov_b64_e32 v[0:1], s[60:61]
	v_mad_i64_i32 v[16:17], s[44:45], v36, s63, v[0:1]
	v_lshl_add_u64 v[0:1], v[16:17], 0, s[42:43]
	s_mov_b32 s11, s43
	v_lshl_add_u64 v[12:13], s[64:65], 1, v[0:1]
	v_lshl_add_u64 v[16:17], v[16:17], 0, s[10:11]
	s_mov_b32 s13, s43
	global_load_dwordx4 v[0:3], v[12:13], off offset:16
	global_load_dwordx4 v[4:7], v[12:13], off
	global_load_dwordx4 v[8:11], v[12:13], off offset:1040
	s_nop 0
	global_load_dwordx4 v[12:15], v[12:13], off offset:1024
	v_lshl_add_u64 v[16:17], v[16:17], 0, s[12:13]
	v_lshl_add_u64 v[16:17], s[72:73], 1, v[16:17]
	global_load_dwordx4 v[16:19], v[16:17], off offset:2048
	s_and_b64 vcc, exec, s[0:1]
	s_cbranch_vccnz .LBB0_360
	v_ashrrev_i32_e32 v37, 31, v36
	v_lshlrev_b64 v[36:37], 5, v[36:37]
	v_lshl_add_u64 v[36:37], s[96:97], 0, v[36:37]
	global_load_dword v84, v[36:37], off
	global_load_dword v85, v[36:37], off offset:16

; DEVI unsigned pk_bf16(float lo, float hi) { unsigned r; asm("v_cvt_pk_bf16_f32 %0, %1, %2" : "=v"(r) : "v"(lo), "v"(hi)); return r; }
; DEVI float bf_lo(unsigned u) { return __uint_as_float(u << 16); }
; DEVI float bf_hi(unsigned u) { return __uint_as_float(u & 0xffff0000u); }
; #define LBAR() do { asm volatile("s_waitcnt lgkmcnt(0)" ::: "memory"); __builtin_amdgcn_s_barrier(); asm volatile("" ::: "memory"); } while (0)
; __device__ __forceinline__ void rglru_item8(const Params& p, unsigned char* lds, int item) {
;     ...
;     LBAR();
; #pragma unroll
;     for (int i = 0; i < 2; ++i) *(uint4*)(raw + (3 + prow + 32 * i) * 136 + pch * 8) = rx[i];
;     LBAR();
;     {
;       const int tr = tid >> 3, cp = tid & 7;
; #pragma unroll
;       for (int c8 = 0; c8 < 2; ++c8) {
;         const int c0 = cp * 16 + c8 * 8; float o[8];
; #pragma unroll
;         for (int j = 0; j < 8; ++j) o[j] = cw[512 + c0 + j];
; #pragma unroll
;         for (int k = 0; k < 4; ++k) { const uint4 xv = *(const uint4*)(raw + (tr + k) * 136 + c0); const float* wp = cw + k * 128 + c0;
;           o[0] += wp[0] * bf_lo(xv.x); o[1] += wp[1] * bf_hi(xv.x); o[2] += wp[2] * bf_lo(xv.y); o[3] += wp[3] * bf_hi(xv.y);
;           o[4] += wp[4] * bf_lo(xv.z); o[5] += wp[5] * bf_hi(xv.z); o[6] += wp[6] * bf_lo(xv.w); o[7] += wp[7] * bf_hi(xv.w); }
;         *(uint4*)(xcA + tr * 136 + c0) = make_uint4(pk_bf16(o[0], o[1]), pk_bf16(o[2], o[3]), pk_bf16(o[4], o[5]), pk_bf16(o[6], o[7]));
;         if ((cp >> 2) == h2) {
; #pragma unroll
;           for (int j = 0; j < 8; ++j) xcF[tr * 65 + (c0 - 64 * h2) + j] = o[j]; }
.LBB0_543:
	s_waitcnt lgkmcnt(0)
	s_barrier
	s_sub_u32 s98, s75, 0x80
	s_cmpk_le_u32 s98, 0xe80
	s_cbranch_scc1 .Lrg_fastA
	s_waitcnt vmcnt(0)
	s_branch .Lrg_joinA
.Lrg_fastA:
	s_waitcnt vmcnt(16)
.Lrg_joinA:
	ds_write_b128 v140, v[64:67] offset:816
	ds_write_b128 v140, v[68:71] offset:9520
	s_waitcnt lgkmcnt(0)
	s_barrier
	ds_read_b128 v[80:83], v142
	ds_read_b128 v[88:91], v142 offset:544
	s_waitcnt lgkmcnt(1)
	v_lshlrev_b32_e32 v94, 16, v80
	v_and_b32_e32 v95, 0xffff0000, v80
	v_lshlrev_b32_e32 v202, 16, v81
	v_and_b32_e32 v203, 0xffff0000, v81
	v_lshlrev_b32_e32 v86, 16, v82
	v_and_b32_e32 v87, 0xffff0000, v82
	v_lshlrev_b32_e32 v80, 16, v83
	v_and_b32_e32 v81, 0xffff0000, v83
	ds_read_b128 v[82:85], v142 offset:272
	s_waitcnt lgkmcnt(1)
	v_lshlrev_b32_e32 v210, 16, v90
	v_and_b32_e32 v211, 0xffff0000, v90
	v_lshlrev_b32_e32 v198, 16, v88
	v_and_b32_e32 v199, 0xffff0000, v88
	s_waitcnt lgkmcnt(0)
	v_lshlrev_b32_e32 v194, 16, v82
	v_and_b32_e32 v195, 0xffff0000, v82
	v_lshlrev_b32_e32 v204, 16, v83
	v_and_b32_e32 v205, 0xffff0000, v83
	v_lshlrev_b32_e32 v206, 16, v84
	v_and_b32_e32 v207, 0xffff0000, v84
	v_lshlrev_b32_e32 v82, 16, v85
	v_and_b32_e32 v83, 0xffff0000, v85
	v_lshlrev_b32_e32 v84, 16, v91
	v_and_b32_e32 v85, 0xffff0000, v91
	ds_read_b128 v[90:93], v142 offset:816
	ds_read_b128 v[104:107], v141 offset:2048
	ds_read_b128 v[182:185], v141
	ds_read_b128 v[186:189], v141 offset:16
	ds_read_b128 v[190:193], v141 offset:512
	v_lshlrev_b32_e32 v208, 16, v89
	v_and_b32_e32 v209, 0xffff0000, v89
	s_waitcnt lgkmcnt(2)
	v_pk_fma_f32 v[94:95], v[182:183], v[94:95], v[104:105]
	v_lshlrev_b32_e32 v88, 16, v90
	s_waitcnt lgkmcnt(0)
	v_pk_fma_f32 v[94:95], v[190:191], v[194:195], v[94:95]
	ds_read_b128 v[194:197], v141 offset:1024
	v_and_b32_e32 v89, 0xffff0000, v90
	v_lshlrev_b32_e32 v90, 16, v91
	v_and_b32_e32 v91, 0xffff0000, v91
	s_waitcnt lgkmcnt(0)
	v_pk_fma_f32 v[94:95], v[194:195], v[198:199], v[94:95]
	ds_read_b128 v[198:201], v141 offset:1536
	s_waitcnt lgkmcnt(0)
	v_pk_fma_f32 v[88:89], v[198:199], v[88:89], v[94:95]
	v_pk_fma_f32 v[94:95], v[184:185], v[202:203], v[106:107]
	ds_read_b128 v[104:107], v141 offset:2064
	ds_read_b128 v[182:185], v141 offset:528
	v_pk_fma_f32 v[94:95], v[192:193], v[204:205], v[94:95]
	ds_read_b128 v[190:193], v141 offset:1040
	v_pk_fma_f32 v[94:95], v[196:197], v[208:209], v[94:95]
	ds_read_b128 v[194:197], v141 offset:1552
	s_waitcnt lgkmcnt(3)
	v_pk_fma_f32 v[86:87], v[186:187], v[86:87], v[104:105]
	v_pk_fma_f32 v[80:81], v[188:189], v[80:81], v[106:107]
	s_waitcnt lgkmcnt(2)
	v_pk_fma_f32 v[86:87], v[182:183], v[206:207], v[86:87]
	v_pk_fma_f32 v[80:81], v[184:185], v[82:83], v[80:81]
	v_pk_fma_f32 v[90:91], v[200:201], v[90:91], v[94:95]
	v_lshlrev_b32_e32 v94, 16, v92
	v_and_b32_e32 v95, 0xffff0000, v92
	s_waitcnt lgkmcnt(1)
	v_pk_fma_f32 v[86:87], v[190:191], v[210:211], v[86:87]
	v_lshlrev_b32_e32 v92, 16, v93
	v_and_b32_e32 v93, 0xffff0000, v93
	v_pk_fma_f32 v[80:81], v[192:193], v[84:85], v[80:81]
	s_waitcnt lgkmcnt(0)
	v_pk_fma_f32 v[86:87], v[194:195], v[94:95], v[86:87]
	v_pk_fma_f32 v[80:81], v[196:197], v[92:93], v[80:81]
	v_cvt_pk_bf16_f32 v82, v88, v89
	v_cvt_pk_bf16_f32 v83, v90, v91
	v_cvt_pk_bf16_f32 v84, v86, v87
	s_nop 0
	v_cvt_pk_bf16_f32 v85, v80, v81
	ds_write_b128 v142, v[82:85] offset:18224
	s_and_saveexec_b64 s[6:7], s[2:3]
	s_cbranch_execz .LBB0_545
	v_add_u32_e32 v82, 0x8b30, v143
	ds_write2_b32 v82, v88, v89 offset1:1
	v_add_u32_e32 v82, 0x8b38, v143
	ds_write2_b32 v82, v90, v91 offset1:1
	v_add_u32_e32 v82, 0x8b40, v143
	ds_write2_b32 v82, v86, v87 offset1:1
	v_add_u32_e32 v82, 0x8b48, v143
	ds_write2_b32 v82, v80, v81 offset1:1

; DEVI unsigned pk_bf16(float lo, float hi) { unsigned r; asm("v_cvt_pk_bf16_f32 %0, %1, %2" : "=v"(r) : "v"(lo), "v"(hi)); return r; }
; DEVI float bf_lo(unsigned u) { return __uint_as_float(u << 16); }
; DEVI float bf_hi(unsigned u) { return __uint_as_float(u & 0xffff0000u); }
; #define LBAR() do { asm volatile("s_waitcnt lgkmcnt(0)" ::: "memory"); __builtin_amdgcn_s_barrier(); asm volatile("" ::: "memory"); } while (0)
; __device__ __forceinline__ void rglru_item8(const Params& p, unsigned char* lds, int item) {
;     ...
;     LBAR();
; #pragma unroll
;     for (int i = 0; i < 2; ++i) *(uint4*)(raw + (3 + prow + 32 * i) * 136 + pch * 8) = rx[i];
;     LBAR();
;     {
;       const int tr = tid >> 3, cp = tid & 7;
; #pragma unroll
;       for (int c8 = 0; c8 < 2; ++c8) {
;         const int c0 = cp * 16 + c8 * 8; float o[8];
; #pragma unroll
;         for (int j = 0; j < 8; ++j) o[j] = cw[512 + c0 + j];
; #pragma unroll
;         for (int k = 0; k < 4; ++k) { const uint4 xv = *(const uint4*)(raw + (tr + k) * 136 + c0); const float* wp = cw + k * 128 + c0;
;           o[0] += wp[0] * bf_lo(xv.x); o[1] += wp[1] * bf_hi(xv.x); o[2] += wp[2] * bf_lo(xv.y); o[3] += wp[3] * bf_hi(xv.y);
;           o[4] += wp[4] * bf_lo(xv.z); o[5] += wp[5] * bf_hi(xv.z); o[6] += wp[6] * bf_lo(xv.w); o[7] += wp[7] * bf_hi(xv.w); }
;         *(uint4*)(xcA + tr * 136 + c0) = make_uint4(pk_bf16(o[0], o[1]), pk_bf16(o[2], o[3]), pk_bf16(o[4], o[5]), pk_bf16(o[6], o[7]));
;         if ((cp >> 2) == h2) {
; #pragma unroll
;           for (int j = 0; j < 8; ++j) xcF[tr * 65 + (c0 - 64 * h2) + j] = o[j]; }
;     ...
;   for (int ti = 0; ti < 65; ti += 2) {
;     tile_step(ti, rxA, gbA);
;     if (ti + 1 < 65) tile_step(ti + 1, rxB, gbB);
.LBB0_636:
	s_xor_b32 s62, s92, 1
	s_cmp_gt_u32 s88, 64
	s_cbranch_scc1 .LBB0_541
	s_waitcnt lgkmcnt(0)
	s_barrier
	s_sub_u32 s98, s75, 0x80
	s_cmpk_le_u32 s98, 0xe80
	s_cbranch_scc0 .Lrg_joinB
	s_waitcnt vmcnt(18)
.Lrg_joinB:
	ds_write_b128 v140, v[72:75] offset:816
	ds_write_b128 v140, v[76:79] offset:9520
	s_waitcnt lgkmcnt(0)
	s_barrier
	ds_read_b128 v[80:83], v142
	ds_read_b128 v[88:91], v142 offset:544
	s_waitcnt lgkmcnt(1)
	v_lshlrev_b32_e32 v94, 16, v80
	v_and_b32_e32 v95, 0xffff0000, v80
	v_lshlrev_b32_e32 v106, 16, v81
	v_and_b32_e32 v107, 0xffff0000, v81
	v_lshlrev_b32_e32 v86, 16, v82
	v_and_b32_e32 v87, 0xffff0000, v82
	v_lshlrev_b32_e32 v80, 16, v83
	v_and_b32_e32 v81, 0xffff0000, v83
	ds_read_b128 v[82:85], v142 offset:272
	s_waitcnt lgkmcnt(1)
	v_lshlrev_b32_e32 v214, 16, v90
	v_and_b32_e32 v215, 0xffff0000, v90
	v_lshlrev_b32_e32 v204, 16, v88
	v_and_b32_e32 v205, 0xffff0000, v88
	s_waitcnt lgkmcnt(0)
	v_lshlrev_b32_e32 v200, 16, v82
	v_and_b32_e32 v201, 0xffff0000, v82
	v_lshlrev_b32_e32 v208, 16, v83
	v_and_b32_e32 v209, 0xffff0000, v83
	v_lshlrev_b32_e32 v210, 16, v84
	v_and_b32_e32 v211, 0xffff0000, v84
	v_lshlrev_b32_e32 v82, 16, v85
	v_and_b32_e32 v83, 0xffff0000, v85
	v_lshlrev_b32_e32 v84, 16, v91
	v_and_b32_e32 v85, 0xffff0000, v91
	ds_read_b128 v[90:93], v142 offset:816
	ds_read_b128 v[184:187], v141 offset:2048
	ds_read_b128 v[188:191], v141
	ds_read_b128 v[192:195], v141 offset:16
	ds_read_b128 v[196:199], v141 offset:512
	v_lshlrev_b32_e32 v212, 16, v89
	v_and_b32_e32 v213, 0xffff0000, v89
	s_waitcnt lgkmcnt(2)
	v_pk_fma_f32 v[94:95], v[188:189], v[94:95], v[184:185]
	v_lshlrev_b32_e32 v88, 16, v90
	s_waitcnt lgkmcnt(0)
	v_pk_fma_f32 v[94:95], v[196:197], v[200:201], v[94:95]
	ds_read_b128 v[200:203], v141 offset:1024
	v_and_b32_e32 v89, 0xffff0000, v90
	v_lshlrev_b32_e32 v90, 16, v91
	v_and_b32_e32 v91, 0xffff0000, v91
	s_waitcnt lgkmcnt(0)
	v_pk_fma_f32 v[94:95], v[200:201], v[204:205], v[94:95]
	ds_read_b128 v[204:207], v141 offset:1536
	s_waitcnt lgkmcnt(0)
	v_pk_fma_f32 v[88:89], v[204:205], v[88:89], v[94:95]
	v_pk_fma_f32 v[94:95], v[190:191], v[106:107], v[186:187]
	ds_read_b128 v[184:187], v141 offset:2064
	ds_read_b128 v[188:191], v141 offset:528
	v_pk_fma_f32 v[94:95], v[198:199], v[208:209], v[94:95]
	ds_read_b128 v[196:199], v141 offset:1040
	v_pk_fma_f32 v[94:95], v[202:203], v[212:213], v[94:95]
	ds_read_b128 v[200:203], v141 offset:1552
	s_waitcnt lgkmcnt(3)
	v_pk_fma_f32 v[86:87], v[192:193], v[86:87], v[184:185]
	v_pk_fma_f32 v[80:81], v[194:195], v[80:81], v[186:187]
	s_waitcnt lgkmcnt(2)
	v_pk_fma_f32 v[86:87], v[188:189], v[210:211], v[86:87]
	v_pk_fma_f32 v[80:81], v[190:191], v[82:83], v[80:81]
	v_pk_fma_f32 v[90:91], v[206:207], v[90:91], v[94:95]
	v_lshlrev_b32_e32 v94, 16, v92
	v_and_b32_e32 v95, 0xffff0000, v92
	s_waitcnt lgkmcnt(1)
	v_pk_fma_f32 v[86:87], v[196:197], v[214:215], v[86:87]
	v_lshlrev_b32_e32 v92, 16, v93
	v_and_b32_e32 v93, 0xffff0000, v93
	v_pk_fma_f32 v[80:81], v[198:199], v[84:85], v[80:81]
	s_waitcnt lgkmcnt(0)
	v_pk_fma_f32 v[86:87], v[200:201], v[94:95], v[86:87]
	v_pk_fma_f32 v[80:81], v[202:203], v[92:93], v[80:81]
	v_cvt_pk_bf16_f32 v82, v88, v89
	v_cvt_pk_bf16_f32 v83, v90, v91
	v_cvt_pk_bf16_f32 v84, v86, v87
	s_nop 0
	v_cvt_pk_bf16_f32 v85, v80, v81
	ds_write_b128 v142, v[82:85] offset:18224
	s_and_saveexec_b64 s[40:41], s[2:3]
	s_cbranch_execz .LBB0_639
	v_add_u32_e32 v82, 0x8b30, v143
	ds_write2_b32 v82, v88, v89 offset1:1
	v_add_u32_e32 v82, 0x8b38, v143
	ds_write2_b32 v82, v90, v91 offset1:1
	v_add_u32_e32 v82, 0x8b40, v143
	ds_write2_b32 v82, v86, v87 offset1:1
	v_add_u32_e32 v82, 0x8b48, v143
	ds_write2_b32 v82, v80, v81 offset1:1

; __global__ void __launch_bounds__(NT, 2) fwd_megakernel(Params p) {
;   cg::grid_group grid = cg::this_grid();
;   __shared__ __attribute__((aligned(16))) unsigned char smem[SMEM_BYTES];
	.amdhsa_kernel _Z14fwd_megakernel6Params
		.amdhsa_group_segment_fixed_size 139284
		.amdhsa_private_segment_fixed_size 0
		.amdhsa_kernarg_size 528
		.amdhsa_user_sgpr_count 2
		.amdhsa_user_sgpr_dispatch_ptr 0
		.amdhsa_user_sgpr_queue_ptr 0
		.amdhsa_user_sgpr_kernarg_segment_ptr 1
		.amdhsa_user_sgpr_dispatch_id 0
		.amdhsa_user_sgpr_kernarg_preload_length 0
		.amdhsa_user_sgpr_kernarg_preload_offset 0
		.amdhsa_user_sgpr_private_segment_size 0
		.amdhsa_uses_dynamic_stack 0
		.amdhsa_enable_private_segment 0
		.amdhsa_system_sgpr_workgroup_id_x 1
		.amdhsa_system_sgpr_workgroup_id_y 0
		.amdhsa_system_sgpr_workgroup_id_z 0
		.amdhsa_system_sgpr_workgroup_info 0
		.amdhsa_system_vgpr_workitem_id 2
		.amdhsa_next_free_vgpr 256
		.amdhsa_next_free_sgpr 102
		.amdhsa_accum_offset 256
		.amdhsa_reserve_vcc 1
		.amdhsa_float_round_mode_32 0
		.amdhsa_float_round_mode_16_64 0
		.amdhsa_float_denorm_mode_32 3
		.amdhsa_float_denorm_mode_16_64 3
		.amdhsa_dx10_clamp 1
		.amdhsa_ieee_mode 1
		.amdhsa_fp16_overflow 0
		.amdhsa_tg_split 0
		.amdhsa_exception_fp_ieee_invalid_op 0
		.amdhsa_exception_fp_denorm_src 0
		.amdhsa_exception_fp_ieee_div_zero 0
		.amdhsa_exception_fp_ieee_overflow 0
		.amdhsa_exception_fp_ieee_underflow 0
		.amdhsa_exception_fp_ieee_inexact 0
		.amdhsa_exception_int_div_zero 0
	.end_amdhsa_kernel

; __global__ void __launch_bounds__(NT, 2) fwd_megakernel(Params p) {
;   cg::grid_group grid = cg::this_grid();
;   __shared__ __attribute__((aligned(16))) unsigned char smem[SMEM_BYTES];
.Lfunc_end0:
	.size	_Z14fwd_megakernel6Params, .Lfunc_end0-_Z14fwd_megakernel6Params
	.set _Z14fwd_megakernel6Params.num_vgpr, 256
	.set _Z14fwd_megakernel6Params.num_agpr, 0
	.set _Z14fwd_megakernel6Params.numbered_sgpr, 102
	.set _Z14fwd_megakernel6Params.num_named_barrier, 0
	.set _Z14fwd_megakernel6Params.private_seg_size, 0
	.set _Z14fwd_megakernel6Params.uses_vcc, 1
	.set _Z14fwd_megakernel6Params.uses_flat_scratch, 0
	.set _Z14fwd_megakernel6Params.has_dyn_sized_stack, 0
	.set _Z14fwd_megakernel6Params.has_recursion, 0
	.set _Z14fwd_megakernel6Params.has_indirect_call, 0

; __global__ void __launch_bounds__(NT, 2) fwd_megakernel(Params p) {
;   cg::grid_group grid = cg::this_grid();
;   __shared__ __attribute__((aligned(16))) unsigned char smem[SMEM_BYTES];
amdhsa.kernels:
  - .agpr_count:     0
    .args:
      - .offset:         0
        .size:           272
        .value_kind:     by_value
      - .offset:         272
        .size:           4
        .value_kind:     hidden_block_count_x
      - .offset:         276
        .size:           4
        .value_kind:     hidden_block_count_y
      - .offset:         280
        .size:           4
        .value_kind:     hidden_block_count_z
      - .offset:         284
        .size:           2
        .value_kind:     hidden_group_size_x
      - .offset:         286
        .size:           2
        .value_kind:     hidden_group_size_y
      - .offset:         288
        .size:           2
        .value_kind:     hidden_group_size_z
      - .offset:         290
        .size:           2
        .value_kind:     hidden_remainder_x
      - .offset:         292
        .size:           2
        .value_kind:     hidden_remainder_y
      - .offset:         294
        .size:           2
        .value_kind:     hidden_remainder_z
      - .offset:         312
        .size:           8
        .value_kind:     hidden_global_offset_x
      - .offset:         320
        .size:           8
        .value_kind:     hidden_global_offset_y
      - .offset:         328
        .size:           8
        .value_kind:     hidden_global_offset_z
      - .offset:         336
        .size:           2
        .value_kind:     hidden_grid_dims
      - .offset:         360
        .size:           8
        .value_kind:     hidden_multigrid_sync_arg
    .group_segment_fixed_size: 139284
    .kernarg_segment_align: 8
    .kernarg_segment_size: 528
    .language:       OpenCL C
    .language_version:
      - 2
      - 0
    .max_flat_workgroup_size: 512
    .name:           _Z14fwd_megakernel6Params
    .private_segment_fixed_size: 0
    .sgpr_count:     108
    .sgpr_spill_count: 156
    .symbol:         _Z14fwd_megakernel6Params.kd
    .uniform_work_group_size: 1
    .uses_dynamic_stack: false
    .vgpr_count:     256
    .vgpr_spill_count: 0
    .wavefront_size: 64
